# phase 3 queue: the 64 serial carry-scan / compress-GEMM items handed out right after the delta-rule chains instead of last
# speedup vs baseline: 1.0006x; 1.0006x over previous
; DI int TID() { int t = threadIdx.x; asm volatile("" : "+v"(t)); return t; }
; DI unsigned char* WSP(const Params& P) { size_t z = 0; asm volatile("" : "+s"(z)); return P.ws + z; }
; DI void cmp2_tile(const Params& P, int l, int ct, u16* sA, u16* sB, float* sSS) {
;   const int tid = TID(), lane = tid & 63, w = tid >> 6, r16 = lane & 15, quad = lane >> 4, wm = w >> 1, wn = w & 1;
;   const int kv = ct >> 4, mt = ct & 15;
;   const u16* HID = (const u16*)(WSP(P) + WS_HID);
;   u16* OUT = (u16*)(WSP(P) + (kv ? WS_VC : WS_KC));
;   const u16* Ab = HID + ((long)kv * 2048 + mt * 128) * 256;
;   const u16* Bb = (const u16*)(WSP(P) + WS_W + WT_C2) + (long)kv * 64 * 256;
;   f32x4 acc[4][2];
;   gemm3<2>(acc, g3_ptr(Ab, 256, tid, 0, false), g3_ptr(Ab, 256, tid, 1, false), g3_ptr(Ab, 256, tid, 2, false), g3_ptr(Ab, 256, tid, 3, false), 64,
;            g3_ptr(Bb, 256, tid, 0, true), g3_ptr(Bb, 256, tid, 1, true), nullptr, nullptr, 256, sA);
; __global__ void __launch_bounds__(256, LB2) fwd_megakernel(Params P) {
;     ...
;       case 3: if (PHASE_MASK & (1 << 3)) {
;         for (;;) {
;           int it = next_item(pc, &s_item); if (it >= 128 + 3072 + 64) break;
;           if (it < 128) gdn_p2_item(P, it, lds);
;           else if (it < 128 + 2048) sb_attn_item(P, it - 128, aQ, aK, aV);
;           else if (it < 128 + 3072) win_attn_item(P, it - 128 - 2048, aQ, aK, aV);
;           else if (it < 128 + 3072 + 32) s5_carry_item(P, l, it - 128 - 3072);
;           else cmp2_tile(P, l, it - 128 - 3072 - 32, sA, sB, lds + 17000);
;         }
.LBB0_266:
	s_or_b64 exec, exec, s[0:1]
	s_waitcnt lgkmcnt(0)
	s_barrier
	ds_read_b32 v0, v165
	s_movk_i32 s0, 0xcbf
	s_movk_i32 s4, 0xc00
	s_waitcnt lgkmcnt(0)
	v_add_u32_e32 v1, 0xffffff80, v0
	v_add_u32_e32 v2, 0xc00, v0
	v_add_u32_e32 v3, 0xfffffbc0, v0
	s_movk_i32 s4, 0xc40
	v_cmp_gt_u32_e64 s[2:3], s4, v1
	v_cmp_gt_u32_e32 vcc, 64, v1
	s_nop 1
	v_cndmask_b32_e64 v3, v0, v3, s[2:3]
	s_movk_i32 s4, 0x440
	v_cndmask_b32_e32 v3, v3, v2, vcc
	v_add_u32_e32 v2, 0x7c0, v0
	v_cmp_gt_u32_e64 s[2:3], s4, v1
	v_cmp_le_u32_e32 vcc, 64, v1
	s_nop 1
	s_and_b64 vcc, vcc, s[2:3]
	s_nop 1
	v_cndmask_b32_e32 v0, v3, v2, vcc
	v_cmp_lt_i32_e32 vcc, s0, v0
	v_readfirstlane_b32 s40, v0
	s_mov_b64 s[0:1], -1
	s_cbranch_vccnz .LBB0_261
	s_cmpk_gt_i32 s40, 0x7f
	s_cbranch_scc0 .LBB0_484
	s_cmpk_gt_u32 s40, 0x87f
	s_cbranch_scc0 .LBB0_462
	s_cmpk_gt_u32 s40, 0xc7f
	s_cbranch_scc0 .LBB0_442
	s_cmpk_gt_u32 s40, 0xc9f
	s_cbranch_scc0 .LBB0_438
	s_add_i32 s7, s40, 0xfffff360
	s_waitcnt vmcnt(6)
	v_mov_b32_e32 v44, v160
	s_lshr_b32 s46, s7, 4
	s_mov_b64 s[0:1], 0
	s_add_u32 s8, s70, s0
	s_addc_u32 s9, s71, s1
	s_lshl_b32 s4, s7, 7
	s_and_b32 s6, s4, 0x780
	s_lshl_b64 s[4:5], s[46:47], 20
	v_ashrrev_i32_e32 v10, 6, v44
	v_lshrrev_b32_e32 v1, 3, v44
	v_bfe_u32 v11, v44, 3, 3
	s_add_u32 s4, s8, s4
	v_lshl_or_b32 v0, v10, 5, v11
	v_bfe_u32 v1, v1, 1, 2
	s_addc_u32 s5, s9, s5
	s_lshl_b32 s8, s6, 9
	v_xor_b32_e32 v4, v1, v44
	v_ashrrev_i32_e32 v1, 31, v0
	s_add_u32 s4, s4, s8
	v_lshlrev_b64 v[2:3], 9, v[0:1]
	v_lshlrev_b32_e32 v1, 4, v4
	v_or_b32_e32 v4, 8, v0
	s_addc_u32 s5, s5, 0
	v_and_b32_e32 v162, 0x70, v1
	v_lshrrev_b32_e32 v1, 1, v4
	s_add_u32 s4, s4, 0x1ce00000
	v_xor_b32_e32 v1, v1, v44
	v_ashrrev_i32_e32 v5, 31, v4
	s_addc_u32 s5, s5, 0
	v_lshlrev_b64 v[4:5], 9, v[4:5]
	v_lshlrev_b32_e32 v1, 4, v1
	v_lshl_add_u64 v[4:5], s[4:5], 0, v[4:5]
	v_and_b32_e32 v6, 0x70, v1
	v_mov_b32_e32 v7, v163
	v_lshl_add_u64 v[4:5], v[4:5], 0, v[6:7]
	v_or_b32_e32 v6, 16, v0
	v_or_b32_e32 v0, 24, v0
	v_lshrrev_b32_e32 v1, 1, v0
	v_xor_b32_e32 v8, v1, v44
	v_ashrrev_i32_e32 v1, 31, v0
	s_mov_b64 s[0:1], 0
	s_mov_b64 s[8:9], 0
	v_lshlrev_b64 v[0:1], 9, v[0:1]
	v_lshlrev_b32_e32 v8, 4, v8
	s_add_u32 s10, s70, s8
	v_lshl_add_u64 v[0:1], s[4:5], 0, v[0:1]
	v_and_b32_e32 v8, 0x70, v8
	v_mov_b32_e32 v9, v163
	s_addc_u32 s11, s71, s9
	s_lshl_b64 s[8:9], s[46:47], 15
	v_lshl_add_u64 v[0:1], v[0:1], 0, v[8:9]
	v_lshl_or_b32 v8, v10, 4, v11
	s_add_u32 s8, s10, s8
	v_ashrrev_i32_e32 v9, 31, v8
	s_addc_u32 s9, s11, s9
	v_lshlrev_b64 v[10:11], 9, v[8:9]
	v_or_b32_e32 v8, 8, v8
	s_add_u32 s8, s8, 0x1f540000
	v_ashrrev_i32_e32 v7, 31, v6
	v_lshrrev_b32_e32 v9, 1, v8
	s_addc_u32 s9, s9, 0
	v_lshlrev_b64 v[6:7], 9, v[6:7]
	s_waitcnt vmcnt(4)
	v_xor_b32_e32 v12, v9, v44
	v_lshl_add_u64 v[2:3], s[4:5], 0, v[2:3]
	v_lshl_add_u64 v[6:7], s[4:5], 0, v[6:7]
	v_lshl_add_u64 v[10:11], s[8:9], 0, v[10:11]
	v_lshlrev_b32_e32 v12, 4, v12
	v_lshl_add_u64 v[2:3], v[2:3], 0, v[162:163]
	v_lshl_add_u64 v[6:7], v[6:7], 0, v[162:163]
	v_lshl_add_u64 v[10:11], v[10:11], 0, v[162:163]
	v_and_b32_e32 v162, 0x70, v12
	v_mov_b32_e32 v12, v160
	v_ashrrev_i32_e32 v9, 31, v8
	v_ashrrev_i32_e32 v13, 6, v12
	v_lshlrev_b64 v[8:9], 9, v[8:9]
	v_readfirstlane_b32 s5, v13
	s_barrier
	s_lshl_b32 s4, s5, 12
	s_mov_b32 m0, s4
	s_nop 0
	global_load_lds_dwordx4 v[2:3], off
	v_lshl_add_u64 v[8:9], s[8:9], 0, v[8:9]
	s_add_i32 s9, s4, 0x400
	s_mov_b32 m0, s9
	s_nop 0
	global_load_lds_dwordx4 v[4:5], off
	s_add_i32 s9, s4, 0x800
	s_mov_b32 m0, s9
	s_nop 0
	global_load_lds_dwordx4 v[6:7], off
	s_lshl_b32 s8, s5, 11
	s_add_i32 s9, s4, 0xc00
	s_mov_b32 m0, s9
	s_nop 0
	global_load_lds_dwordx4 v[0:1], off
	s_add_i32 s5, s8, 0x4000
	s_mov_b32 m0, s5
	s_nop 0
	global_load_lds_dwordx4 v[10:11], off
	s_addk_i32 s8, 0x4400
	v_lshl_add_u64 v[8:9], v[8:9], 0, v[162:163]
	v_lshrrev_b32_e32 v15, 1, v12
	v_and_b32_e32 v17, 15, v12
	s_mov_b32 m0, s8
	s_nop 0
	global_load_lds_dwordx4 v[8:9], off
	s_mov_b32 s8, 0x1ffffc0
	v_lshrrev_b32_e32 v14, 4, v12
	v_bfe_u32 v16, v12, 1, 3
	v_bfe_u32 v12, v12, 4, 2
	v_and_or_b32 v15, v15, s8, v17
	v_lshlrev_b32_e32 v13, 5, v13
	s_mov_b64 s[8:9], 0x80
	v_and_or_b32 v13, v13, 32, v17
	v_bitop3_b32 v14, v14, v16, 3 bitop3:0x6c
	v_bitop3_b32 v12, v12, v16, 4 bitop3:0x36
	v_lshl_add_u64 v[36:37], v[0:1], 0, s[8:9]
	v_mov_b32_e32 v0, 0
	s_mov_b64 s[2:3], 0
	v_lshlrev_b32_e32 v45, 3, v14
	v_lshlrev_b32_e32 v46, 7, v15
	v_lshlrev_b32_e32 v47, 7, v13
	v_lshlrev_b32_e32 v48, 3, v12
	v_lshl_add_u64 v[32:33], v[8:9], 0, s[8:9]
	v_lshl_add_u64 v[34:35], v[10:11], 0, s[8:9]
	v_lshl_add_u64 v[38:39], v[6:7], 0, s[8:9]
	v_lshl_add_u64 v[40:41], v[4:5], 0, s[8:9]
	v_lshl_add_u64 v[42:43], v[2:3], 0, s[8:9]
	s_mov_b32 s8, 0
	s_mov_b32 s9, 0
	v_mov_b32_e32 v1, v0
	v_mov_b32_e32 v2, v0
	v_mov_b32_e32 v3, v0
	v_mov_b32_e32 v4, v0
	v_mov_b32_e32 v5, v0
	v_mov_b32_e32 v6, v0
	v_mov_b32_e32 v7, v0
	v_mov_b32_e32 v8, v0
	v_mov_b32_e32 v9, v0
	v_mov_b32_e32 v10, v0
	v_mov_b32_e32 v11, v0
	v_mov_b32_e32 v12, v0
	v_mov_b32_e32 v13, v0
	v_mov_b32_e32 v14, v0
	v_mov_b32_e32 v15, v0
	v_mov_b32_e32 v16, v0
	v_mov_b32_e32 v17, v0
	v_mov_b32_e32 v18, v0
	v_mov_b32_e32 v19, v0
	v_mov_b32_e32 v20, v0
	v_mov_b32_e32 v21, v0
	v_mov_b32_e32 v22, v0
	v_mov_b32_e32 v23, v0
	v_mov_b32_e32 v24, v0
	v_mov_b32_e32 v25, v0
	v_mov_b32_e32 v26, v0
	v_mov_b32_e32 v27, v0
	v_mov_b32_e32 v28, v0
	v_mov_b32_e32 v29, v0
	v_mov_b32_e32 v30, v0
	v_mov_b32_e32 v31, v0
	s_branch .LBB0_273
